# P5 attention epilogue: ds_bpermute ladder replaced by DPP quad swap + v_perm pack, all-lane dword stores
# speedup vs baseline: 1.0057x; 1.0057x over previous
; __device__ __forceinline__ void partialSM(f32x16& p0, f32x16& p1, float& m_reg, float& mn, float& alpha) {
;     ...
;     if (__builtin_expect(__all((pmax - m_reg) * SCALE <= THR), 1)) { mn = m_reg; alpha = 1.f; }
;     else { mn = fmaxf(m_reg, pmax); alpha = __builtin_amdgcn_exp2f((m_reg - mn) * C2); m_reg = mn; }
;     const float mnL = -mn * C2;
; #pragma unroll
;     for (int r = 0; r < 16; ++r) p0[r] = fmaf(p0[r], C2, mnL);
; #pragma unroll
;     for (int r = 0; r < 16; ++r) p1[r] = fmaf(p1[r], C2, mnL);
; #pragma unroll
;     for (int r = 0; r < 16; ++r) p0[r] = __builtin_amdgcn_exp2f(p0[r]);
; }
; __device__ __forceinline__ void finishSM(f32x16& p0, f32x16& p1, float alpha, float& l_reg, bf16x8& pa0, bf16x8& pa1, bf16x8& pa2, bf16x8& pa3) {
; #pragma unroll
;     for (int r = 0; r < 16; ++r) p1[r] = __builtin_amdgcn_exp2f(p1[r]);
;     float ps = 0;
; #pragma unroll
;     for (int r = 0; r < 16; ++r) ps += p0[r];
; #pragma unroll
;     for (int r = 0; r < 16; ++r) ps += p1[r];
;     { auto rr = __builtin_amdgcn_permlane32_swap(__float_as_uint(ps), __float_as_uint(ps), false, false);
;       ps = __uint_as_float(rr[0]) + __uint_as_float(rr[1]); }
;     l_reg = l_reg * alpha + ps;
;     ...
;     PK4(p0, 0, pa0); PK4(p0, 8, pa1); PK4(p1, 0, pa2); PK4(p1, 8, pa3);
; template <int VB>
; __device__ __forceinline__ void pv_tile(f32x16* o, int vb0, bf16x8 pa0, bf16x8 pa1, bf16x8 pa2, bf16x8 pa3) {
;     ...
;     PV_D0(0); PV_D0(1); PV_D0(2); PV_D0(3);
.LBB0_1317:
	v_cndmask_b32_e64 v94, v94, v206, s[6:7]
	v_mul_f32_e32 v94, 0xbe0293ee, v94
	v_fmamk_f32 v153, v100, 0x3e0293ee, v94
	v_fmamk_f32 v154, v101, 0x3e0293ee, v94
	v_fmamk_f32 v161, v80, 0x3e0293ee, v94
	v_exp_f32_e32 v80, v153
	v_fmamk_f32 v83, v83, 0x3e0293ee, v94
	v_fmamk_f32 v165, v81, 0x3e0293ee, v94
	v_exp_f32_e32 v81, v154
	v_fmamk_f32 v150, v150, 0x3e0293ee, v94
	v_fmamk_f32 v155, v88, 0x3e0293ee, v94
	v_fmamk_f32 v88, v82, 0x3e0293ee, v94
	v_exp_f32_e32 v82, v83
	v_fmamk_f32 v151, v151, 0x3e0293ee, v94
	v_fmamk_f32 v67, v67, 0x3e0293ee, v94
	v_exp_f32_e32 v83, v150
	v_fmamk_f32 v152, v152, 0x3e0293ee, v94
	v_fmamk_f32 v87, v87, 0x3e0293ee, v94
	v_fmamk_f32 v156, v89, 0x3e0293ee, v94
	v_fmamk_f32 v157, v90, 0x3e0293ee, v94
	v_fmamk_f32 v158, v91, 0x3e0293ee, v94
	v_fmamk_f32 v159, v92, 0x3e0293ee, v94
	v_fmamk_f32 v160, v93, 0x3e0293ee, v94
	v_fmamk_f32 v79, v79, 0x3e0293ee, v94
	v_fmamk_f32 v68, v68, 0x3e0293ee, v94
	v_fmamk_f32 v89, v69, 0x3e0293ee, v94
	v_fmamk_f32 v90, v70, 0x3e0293ee, v94
	v_fmamk_f32 v91, v71, 0x3e0293ee, v94
	v_fmamk_f32 v92, v72, 0x3e0293ee, v94
	v_fmamk_f32 v93, v84, 0x3e0293ee, v94
	v_fmamk_f32 v95, v85, 0x3e0293ee, v94
	v_fmamk_f32 v96, v86, 0x3e0293ee, v94
	v_fmamk_f32 v97, v76, 0x3e0293ee, v94
	v_fmamk_f32 v100, v77, 0x3e0293ee, v94
	v_fmamk_f32 v101, v78, 0x3e0293ee, v94
	v_exp_f32_e32 v84, v151
	v_fmamk_f32 v73, v73, 0x3e0293ee, v94
	v_fmamk_f32 v74, v74, 0x3e0293ee, v94
	v_fmac_f32_e32 v94, 0x3e0293ee, v75
	v_exp_f32_e32 v75, v88
	v_exp_f32_e32 v88, v67
	v_add_f32_e32 v67, 0, v80
	v_exp_f32_e32 v85, v152
	v_add_f32_e32 v67, v81, v67
	v_exp_f32_e32 v86, v87
	v_add_f32_e32 v67, v82, v67
	v_exp_f32_e32 v87, v155
	v_add_f32_e32 v67, v83, v67
	v_exp_f32_e32 v69, v156
	v_add_f32_e32 v67, v84, v67
	v_exp_f32_e32 v70, v157
	v_add_f32_e32 v67, v85, v67
	v_exp_f32_e32 v71, v158
	v_add_f32_e32 v67, v86, v67
	v_exp_f32_e32 v72, v159
	v_add_f32_e32 v67, v87, v67
	v_exp_f32_e32 v76, v160
	v_add_f32_e32 v67, v69, v67
	v_exp_f32_e32 v77, v79
	v_add_f32_e32 v67, v70, v67
	v_exp_f32_e32 v78, v161
	v_add_f32_e32 v67, v71, v67
	v_exp_f32_e32 v79, v165
	v_add_f32_e32 v67, v72, v67
	v_add_f32_e32 v67, v76, v67
	v_add_f32_e32 v67, v77, v67
	v_exp_f32_e32 v150, v68
	v_add_f32_e32 v67, v78, v67
	v_exp_f32_e32 v89, v89
	v_add_f32_e32 v67, v79, v67
	v_exp_f32_e32 v90, v90
	v_add_f32_e32 v67, v75, v67
	v_exp_f32_e32 v91, v91
	v_add_f32_e32 v67, v88, v67
	v_exp_f32_e32 v92, v92
	v_add_f32_e32 v67, v150, v67
	v_exp_f32_e32 v93, v93
	v_add_f32_e32 v67, v89, v67
	v_exp_f32_e32 v95, v95
	v_add_f32_e32 v67, v90, v67
	v_exp_f32_e32 v96, v96
	v_add_f32_e32 v67, v91, v67
	v_exp_f32_e32 v97, v97
	v_add_f32_e32 v67, v92, v67
	v_exp_f32_e32 v100, v100
	v_add_f32_e32 v67, v93, v67
	v_exp_f32_e32 v101, v101
	v_add_f32_e32 v67, v95, v67
	v_exp_f32_e32 v151, v73
	v_add_f32_e32 v67, v96, v67
	v_exp_f32_e32 v152, v74
	v_add_f32_e32 v67, v97, v67
	v_exp_f32_e32 v94, v94
	v_add_f32_e32 v67, v100, v67
	v_add_f32_e32 v67, v101, v67
	v_add_f32_e32 v67, v151, v67
	v_add_f32_e32 v67, v152, v67
	v_add_f32_e32 v67, v94, v67
	v_mov_b32_e32 v68, v67
	s_nop 1
	v_permlane32_swap_b32_e32 v67, v68
	v_cvt_pk_bf16_f32 v80, v80, v81
	v_cvt_pk_bf16_f32 v81, v82, v83
	v_cvt_pk_bf16_f32 v82, v84, v85
	v_cvt_pk_bf16_f32 v83, v86, v87
	v_cvt_pk_bf16_f32 v70, v69, v70
	v_cvt_pk_bf16_f32 v71, v71, v72
	v_cvt_pk_bf16_f32 v72, v76, v77
	v_cvt_pk_bf16_f32 v73, v78, v79
	v_cvt_pk_bf16_f32 v74, v75, v88
	v_cvt_pk_bf16_f32 v75, v150, v89
	v_cvt_pk_bf16_f32 v76, v90, v91
	v_cvt_pk_bf16_f32 v77, v92, v93
	v_cvt_pk_bf16_f32 v84, v95, v96
	v_cvt_pk_bf16_f32 v85, v97, v100
	v_cvt_pk_bf16_f32 v86, v101, v151
	v_cvt_pk_bf16_f32 v87, v152, v94
	v_permlane32_swap_b32_e32 v80, v82
	v_permlane32_swap_b32_e32 v81, v83
	v_permlane32_swap_b32_e32 v70, v72
	v_permlane32_swap_b32_e32 v71, v73
	v_permlane32_swap_b32_e32 v74, v76
	v_permlane32_swap_b32_e32 v75, v77
	v_permlane32_swap_b32_e32 v84, v86
	v_permlane32_swap_b32_e32 v85, v87
	ds_read_b64_tr_b16 v[88:89], v1 offset:0x4000
	ds_read_b64_tr_b16 v[90:91], v1 offset:0x4800
	ds_read_b64_tr_b16 v[92:93], v1 offset:0x5000
	ds_read_b64_tr_b16 v[94:95], v1 offset:0x5800
	ds_read_b64_tr_b16 v[150:151], v1 offset:0x6000
	ds_read_b64_tr_b16 v[152:153], v1 offset:0x6800
	ds_read_b64_tr_b16 v[154:155], v1 offset:0x7000
	ds_read_b64_tr_b16 v[156:157], v1 offset:0x7800
	s_waitcnt lgkmcnt(0)
	s_nop 0
	v_mfma_f32_32x32x16_bf16 v[2:17], v[80:83], v[88:91], v[2:17]
	ds_read_b64_tr_b16 v[88:89], v1 offset:0x4200
	ds_read_b64_tr_b16 v[90:91], v1 offset:0x4a00
	v_mfma_f32_32x32x16_bf16 v[2:17], v[70:73], v[92:95], v[2:17]
	ds_read_b64_tr_b16 v[92:93], v1 offset:0x5200
	ds_read_b64_tr_b16 v[94:95], v1 offset:0x5a00
	v_mfma_f32_32x32x16_bf16 v[2:17], v[74:77], v[150:153], v[2:17]
	ds_read_b64_tr_b16 v[150:151], v1 offset:0x6200
	ds_read_b64_tr_b16 v[152:153], v1 offset:0x6a00
	ds_read_b64_tr_b16 v[158:159], v1 offset:0x7200
	ds_read_b64_tr_b16 v[160:161], v1 offset:0x7a00
	s_waitcnt lgkmcnt(0)
	v_mfma_f32_32x32x16_bf16 v[2:17], v[84:87], v[154:157], v[2:17]
	v_mfma_f32_32x32x16_bf16 v[50:65], v[80:83], v[88:91], v[50:65]
	ds_read_b64_tr_b16 v[88:89], v1 offset:0x4400
	ds_read_b64_tr_b16 v[90:91], v1 offset:0x4c00
	v_mfma_f32_32x32x16_bf16 v[50:65], v[70:73], v[92:95], v[50:65]
	ds_read_b64_tr_b16 v[92:93], v1 offset:0x5400
	ds_read_b64_tr_b16 v[94:95], v1 offset:0x5c00
	v_mfma_f32_32x32x16_bf16 v[50:65], v[74:77], v[150:153], v[50:65]
	ds_read_b64_tr_b16 v[150:151], v1 offset:0x6400
	ds_read_b64_tr_b16 v[152:153], v1 offset:0x6c00
	ds_read_b64_tr_b16 v[154:155], v1 offset:0x7400
	ds_read_b64_tr_b16 v[156:157], v1 offset:0x7c00
	s_waitcnt lgkmcnt(0)
; #define SBAR() __builtin_amdgcn_sched_barrier(0)
; __device__ __forceinline__ int crow(int r, int hi) { return (r & 3) + 8 * (r >> 2) + 4 * hi; }
; __device__ __forceinline__ unsigned cvtpk(float lo, float hi) { return pg8::cvt_pk_bf16(lo, hi); }
; #define SEAM_K0() do { VMWN(NQL); SWRITE_HK(0); SBAR(); } while (0)
; __device__ __forceinline__ void attn_block(const BlockRef& cur, const BlockRef& nxt, char* lds, Seam& S) {
;     ...
;     SBAR(); SEAM_K0();
;     if (hi == 0) li_l[r32] = l_reg; asm volatile("s_waitcnt lgkmcnt(0)" ::: "memory");
;     float rli[16];
; #pragma unroll
;     for (int r = 0; r < 16; ++r) rli[r] = __builtin_amdgcn_rcpf(li_l[crow(r, hi)]);
;     bf16* Ow = cur.O + (size_t)(wid * QBLK) * LD;
; #pragma unroll
;     for (int r = 0; r < 16; ++r) { const int orow = crow(r, hi);
; #pragma unroll
;         for (int d0 = 0; d0 < 4; ++d0) { const float v = o[d0][r] * rli[r];
;             const float vn = __shfl_xor(v, 1);
;             if ((r32 & 1) == 0) *(unsigned*)(Ow + (size_t)orow * LD + d0 * 32 + r32) = cvtpk(v, vn); } }
	v_mfma_f32_32x32x16_bf16 v[50:65], v[84:87], v[158:161], v[50:65]
	v_mfma_f32_32x32x16_bf16 v[34:49], v[80:83], v[88:91], v[34:49]
	ds_read_b64_tr_b16 v[88:89], v1 offset:0x4600
	ds_read_b64_tr_b16 v[90:91], v1 offset:0x4e00
	v_mfma_f32_32x32x16_bf16 v[34:49], v[70:73], v[92:95], v[34:49]
	ds_read_b64_tr_b16 v[92:93], v1 offset:0x5600
	ds_read_b64_tr_b16 v[94:95], v1 offset:0x5e00
	v_mfma_f32_32x32x16_bf16 v[34:49], v[74:77], v[150:153], v[34:49]
	ds_read_b64_tr_b16 v[150:151], v1 offset:0x6600
	ds_read_b64_tr_b16 v[152:153], v1 offset:0x6e00
	ds_read_b64_tr_b16 v[158:159], v1 offset:0x7600
	ds_read_b64_tr_b16 v[160:161], v1 offset:0x7e00
	s_waitcnt lgkmcnt(0)
	v_mfma_f32_32x32x16_bf16 v[34:49], v[84:87], v[154:157], v[34:49]
	v_mfma_f32_32x32x16_bf16 v[18:33], v[80:83], v[88:91], v[18:33]
	v_mfma_f32_32x32x16_bf16 v[18:33], v[70:73], v[92:95], v[18:33]
	v_mfma_f32_32x32x16_bf16 v[18:33], v[74:77], v[150:153], v[18:33]
	v_mfma_f32_32x32x16_bf16 v[18:33], v[84:87], v[158:161], v[18:33]
	s_waitcnt vmcnt(8)
	s_waitcnt vmcnt(9)
	ds_write_b128 v204, v[142:145] offset:32768
	s_waitcnt vmcnt(8)
	ds_write_b128 v204, v[146:149] offset:40960
	s_and_saveexec_b64 s[6:7], s[0:1]
	v_add_f32_e32 v69, v98, v99
	v_fmac_f32_e32 v69, v205, v207
	v_add_f32_e32 v67, v67, v68
	v_fmac_f32_e32 v67, v69, v66
	ds_write_b32 v185, v67
	s_or_b64 exec, exec, s[6:7]
	s_waitcnt lgkmcnt(0)
	ds_read_b128 v[78:81], v183
	ds_read_b128 v[74:77], v183 offset:32
	ds_read_b128 v[70:73], v183 offset:64
	ds_read_b128 v[66:69], v183 offset:96
	s_lshl_b64 s[6:7], s[12:13], 11
	s_add_u32 s6, s66, s6
	s_addc_u32 s7, s67, s7
	v_mov_b32_e32 v84, 0x7fe
	v_cndmask_b32_e64 v84, v84, 0, s[4:5]
	v_add3_u32 v82, v166, v168, v84
	v_mov_b32_e32 v84, 0x3020706
	v_mov_b32_e32 v85, 0x5040100
	v_cndmask_b32_e64 v84, v84, v85, s[4:5]
	s_waitcnt lgkmcnt(0)
	v_rcp_f32_e32 v78, v78
	v_rcp_f32_e32 v79, v79
	v_rcp_f32_e32 v80, v80
	v_rcp_f32_e32 v81, v81
	v_rcp_f32_e32 v74, v74
	v_rcp_f32_e32 v75, v75
	v_rcp_f32_e32 v76, v76
	v_rcp_f32_e32 v77, v77
	v_rcp_f32_e32 v70, v70
	v_rcp_f32_e32 v71, v71
	v_rcp_f32_e32 v72, v72
	v_rcp_f32_e32 v73, v73
	v_rcp_f32_e32 v66, v66
	v_rcp_f32_e32 v67, v67
	v_rcp_f32_e32 v68, v68
	v_rcp_f32_e32 v69, v69
	v_mul_f32_e32 v2, v2, v78
	v_mul_f32_e32 v3, v3, v79
	v_mul_f32_e32 v50, v50, v78
	v_mul_f32_e32 v51, v51, v79
	v_mul_f32_e32 v34, v34, v78
	v_mul_f32_e32 v35, v35, v79
	v_mul_f32_e32 v18, v18, v78
	v_mul_f32_e32 v19, v19, v79
	v_cvt_pk_bf16_f32 v2, v2, v3
	v_cvt_pk_bf16_f32 v50, v50, v51
	v_cvt_pk_bf16_f32 v34, v34, v35
	v_cvt_pk_bf16_f32 v18, v18, v19
	v_mov_b32_dpp v3, v2 quad_perm:[1,0,3,2] row_mask:0xf bank_mask:0xf
	v_mov_b32_dpp v51, v50 quad_perm:[1,0,3,2] row_mask:0xf bank_mask:0xf
	v_mov_b32_dpp v35, v34 quad_perm:[1,0,3,2] row_mask:0xf bank_mask:0xf
	v_mov_b32_dpp v19, v18 quad_perm:[1,0,3,2] row_mask:0xf bank_mask:0xf
	v_perm_b32 v2, v3, v2, v84
	v_perm_b32 v50, v51, v50, v84
	v_perm_b32 v34, v35, v34, v84
	v_perm_b32 v18, v19, v18, v84
	global_store_dword v82, v2, s[6:7]
	global_store_dword v82, v50, s[6:7] offset:64
	global_store_dword v82, v34, s[6:7] offset:128
	global_store_dword v82, v18, s[6:7] offset:192
	v_mul_f32_e32 v4, v4, v80
	v_mul_f32_e32 v5, v5, v81
	v_mul_f32_e32 v52, v52, v80
	v_mul_f32_e32 v53, v53, v81
	v_mul_f32_e32 v36, v36, v80
	v_mul_f32_e32 v37, v37, v81
	v_mul_f32_e32 v20, v20, v80
	v_mul_f32_e32 v21, v21, v81
	v_add_u32_e32 v82, 0x1000, v82
	v_cvt_pk_bf16_f32 v4, v4, v5
	v_cvt_pk_bf16_f32 v52, v52, v53
	v_cvt_pk_bf16_f32 v36, v36, v37
	v_cvt_pk_bf16_f32 v20, v20, v21
	v_mov_b32_dpp v5, v4 quad_perm:[1,0,3,2] row_mask:0xf bank_mask:0xf
	v_mov_b32_dpp v53, v52 quad_perm:[1,0,3,2] row_mask:0xf bank_mask:0xf
	v_mov_b32_dpp v37, v36 quad_perm:[1,0,3,2] row_mask:0xf bank_mask:0xf
	v_mov_b32_dpp v21, v20 quad_perm:[1,0,3,2] row_mask:0xf bank_mask:0xf
	v_perm_b32 v4, v5, v4, v84
	v_perm_b32 v52, v53, v52, v84
	v_perm_b32 v36, v37, v36, v84
	v_perm_b32 v20, v21, v20, v84
	global_store_dword v82, v4, s[6:7]
	global_store_dword v82, v52, s[6:7] offset:64
	global_store_dword v82, v36, s[6:7] offset:128
	global_store_dword v82, v20, s[6:7] offset:192
	v_mul_f32_e32 v6, v6, v74
	v_mul_f32_e32 v7, v7, v75
	v_mul_f32_e32 v54, v54, v74
	v_mul_f32_e32 v55, v55, v75
	v_mul_f32_e32 v38, v38, v74
	v_mul_f32_e32 v39, v39, v75
	v_mul_f32_e32 v22, v22, v74
	v_mul_f32_e32 v23, v23, v75
	v_add_u32_e32 v82, 0x3000, v82
	v_cvt_pk_bf16_f32 v6, v6, v7
	v_cvt_pk_bf16_f32 v54, v54, v55
	v_cvt_pk_bf16_f32 v38, v38, v39
	v_cvt_pk_bf16_f32 v22, v22, v23
	v_mov_b32_dpp v7, v6 quad_perm:[1,0,3,2] row_mask:0xf bank_mask:0xf
	v_mov_b32_dpp v55, v54 quad_perm:[1,0,3,2] row_mask:0xf bank_mask:0xf
	v_mov_b32_dpp v39, v38 quad_perm:[1,0,3,2] row_mask:0xf bank_mask:0xf
	v_mov_b32_dpp v23, v22 quad_perm:[1,0,3,2] row_mask:0xf bank_mask:0xf
	v_perm_b32 v6, v7, v6, v84
	v_perm_b32 v54, v55, v54, v84
	v_perm_b32 v38, v39, v38, v84
	v_perm_b32 v22, v23, v22, v84
	global_store_dword v82, v6, s[6:7]
	global_store_dword v82, v54, s[6:7] offset:64
; __device__ __forceinline__ int crow(int r, int hi) { return (r & 3) + 8 * (r >> 2) + 4 * hi; }
; __device__ __forceinline__ unsigned cvtpk(float lo, float hi) { return pg8::cvt_pk_bf16(lo, hi); }
; __device__ __forceinline__ void attn_block(const BlockRef& cur, const BlockRef& nxt, char* lds, Seam& S) {
;     ...
; #pragma unroll
;     for (int r = 0; r < 16; ++r) { const int orow = crow(r, hi);
; #pragma unroll
;         for (int d0 = 0; d0 < 4; ++d0) { const float v = o[d0][r] * rli[r];
;             const float vn = __shfl_xor(v, 1);
;             if ((r32 & 1) == 0) *(unsigned*)(Ow + (size_t)orow * LD + d0 * 32 + r32) = cvtpk(v, vn); } }
	global_store_dword v82, v38, s[6:7] offset:128
	global_store_dword v82, v22, s[6:7] offset:192
	v_mul_f32_e32 v8, v8, v76
	v_mul_f32_e32 v9, v9, v77
	v_mul_f32_e32 v56, v56, v76
	v_mul_f32_e32 v57, v57, v77
	v_mul_f32_e32 v40, v40, v76
	v_mul_f32_e32 v41, v41, v77
	v_mul_f32_e32 v24, v24, v76
	v_mul_f32_e32 v25, v25, v77
	v_add_u32_e32 v82, 0x1000, v82
	v_cvt_pk_bf16_f32 v8, v8, v9
	v_cvt_pk_bf16_f32 v56, v56, v57
	v_cvt_pk_bf16_f32 v40, v40, v41
	v_cvt_pk_bf16_f32 v24, v24, v25
	v_mov_b32_dpp v9, v8 quad_perm:[1,0,3,2] row_mask:0xf bank_mask:0xf
	v_mov_b32_dpp v57, v56 quad_perm:[1,0,3,2] row_mask:0xf bank_mask:0xf
	v_mov_b32_dpp v41, v40 quad_perm:[1,0,3,2] row_mask:0xf bank_mask:0xf
	v_mov_b32_dpp v25, v24 quad_perm:[1,0,3,2] row_mask:0xf bank_mask:0xf
	v_perm_b32 v8, v9, v8, v84
	v_perm_b32 v56, v57, v56, v84
	v_perm_b32 v40, v41, v40, v84
	v_perm_b32 v24, v25, v24, v84
	global_store_dword v82, v8, s[6:7]
	global_store_dword v82, v56, s[6:7] offset:64
	global_store_dword v82, v40, s[6:7] offset:128
	global_store_dword v82, v24, s[6:7] offset:192
	v_mul_f32_e32 v10, v10, v70
	v_mul_f32_e32 v11, v11, v71
	v_mul_f32_e32 v58, v58, v70
	v_mul_f32_e32 v59, v59, v71
	v_mul_f32_e32 v42, v42, v70
	v_mul_f32_e32 v43, v43, v71
	v_mul_f32_e32 v26, v26, v70
	v_mul_f32_e32 v27, v27, v71
	v_add_u32_e32 v82, 0x3000, v82
	v_cvt_pk_bf16_f32 v10, v10, v11
	v_cvt_pk_bf16_f32 v58, v58, v59
	v_cvt_pk_bf16_f32 v42, v42, v43
	v_cvt_pk_bf16_f32 v26, v26, v27
	v_mov_b32_dpp v11, v10 quad_perm:[1,0,3,2] row_mask:0xf bank_mask:0xf
	v_mov_b32_dpp v59, v58 quad_perm:[1,0,3,2] row_mask:0xf bank_mask:0xf
	v_mov_b32_dpp v43, v42 quad_perm:[1,0,3,2] row_mask:0xf bank_mask:0xf
	v_mov_b32_dpp v27, v26 quad_perm:[1,0,3,2] row_mask:0xf bank_mask:0xf
	v_perm_b32 v10, v11, v10, v84
	v_perm_b32 v58, v59, v58, v84
	v_perm_b32 v42, v43, v42, v84
	v_perm_b32 v26, v27, v26, v84
	global_store_dword v82, v10, s[6:7]
	global_store_dword v82, v58, s[6:7] offset:64
	global_store_dword v82, v42, s[6:7] offset:128
	global_store_dword v82, v26, s[6:7] offset:192
	v_mul_f32_e32 v12, v12, v72
	v_mul_f32_e32 v13, v13, v73
	v_mul_f32_e32 v60, v60, v72
	v_mul_f32_e32 v61, v61, v73
	v_mul_f32_e32 v44, v44, v72
	v_mul_f32_e32 v45, v45, v73
	v_mul_f32_e32 v28, v28, v72
	v_mul_f32_e32 v29, v29, v73
	v_add_u32_e32 v82, 0x1000, v82
	v_cvt_pk_bf16_f32 v12, v12, v13
	v_cvt_pk_bf16_f32 v60, v60, v61
	v_cvt_pk_bf16_f32 v44, v44, v45
	v_cvt_pk_bf16_f32 v28, v28, v29
	v_mov_b32_dpp v13, v12 quad_perm:[1,0,3,2] row_mask:0xf bank_mask:0xf
	v_mov_b32_dpp v61, v60 quad_perm:[1,0,3,2] row_mask:0xf bank_mask:0xf
	v_mov_b32_dpp v45, v44 quad_perm:[1,0,3,2] row_mask:0xf bank_mask:0xf
	v_mov_b32_dpp v29, v28 quad_perm:[1,0,3,2] row_mask:0xf bank_mask:0xf
	v_perm_b32 v12, v13, v12, v84
	v_perm_b32 v60, v61, v60, v84
	v_perm_b32 v44, v45, v44, v84
	v_perm_b32 v28, v29, v28, v84
	global_store_dword v82, v12, s[6:7]
	global_store_dword v82, v60, s[6:7] offset:64
	global_store_dword v82, v44, s[6:7] offset:128
	global_store_dword v82, v28, s[6:7] offset:192
	v_mul_f32_e32 v14, v14, v66
	v_mul_f32_e32 v15, v15, v67
	v_mul_f32_e32 v62, v62, v66
	v_mul_f32_e32 v63, v63, v67
	v_mul_f32_e32 v46, v46, v66
	v_mul_f32_e32 v47, v47, v67
	v_mul_f32_e32 v30, v30, v66
	v_mul_f32_e32 v31, v31, v67
	v_add_u32_e32 v82, 0x3000, v82
	v_cvt_pk_bf16_f32 v14, v14, v15
	v_cvt_pk_bf16_f32 v62, v62, v63
	v_cvt_pk_bf16_f32 v46, v46, v47
	v_cvt_pk_bf16_f32 v30, v30, v31
	v_mov_b32_dpp v15, v14 quad_perm:[1,0,3,2] row_mask:0xf bank_mask:0xf
	v_mov_b32_dpp v63, v62 quad_perm:[1,0,3,2] row_mask:0xf bank_mask:0xf
	v_mov_b32_dpp v47, v46 quad_perm:[1,0,3,2] row_mask:0xf bank_mask:0xf
	v_mov_b32_dpp v31, v30 quad_perm:[1,0,3,2] row_mask:0xf bank_mask:0xf
	v_perm_b32 v14, v15, v14, v84
	v_perm_b32 v62, v63, v62, v84
	v_perm_b32 v46, v47, v46, v84
	v_perm_b32 v30, v31, v30, v84
	global_store_dword v82, v14, s[6:7]
	global_store_dword v82, v62, s[6:7] offset:64
	global_store_dword v82, v46, s[6:7] offset:128
	global_store_dword v82, v30, s[6:7] offset:192
	v_mul_f32_e32 v16, v16, v68
	v_mul_f32_e32 v17, v17, v69
	v_mul_f32_e32 v64, v64, v68
	v_mul_f32_e32 v65, v65, v69
	v_mul_f32_e32 v48, v48, v68
	v_mul_f32_e32 v49, v49, v69
	v_mul_f32_e32 v32, v32, v68
	v_mul_f32_e32 v33, v33, v69
	v_add_u32_e32 v82, 0x1000, v82
	v_cvt_pk_bf16_f32 v16, v16, v17
	v_cvt_pk_bf16_f32 v64, v64, v65
	v_cvt_pk_bf16_f32 v48, v48, v49
	v_cvt_pk_bf16_f32 v32, v32, v33
	v_mov_b32_dpp v17, v16 quad_perm:[1,0,3,2] row_mask:0xf bank_mask:0xf
	v_mov_b32_dpp v65, v64 quad_perm:[1,0,3,2] row_mask:0xf bank_mask:0xf
	v_mov_b32_dpp v49, v48 quad_perm:[1,0,3,2] row_mask:0xf bank_mask:0xf
	v_mov_b32_dpp v33, v32 quad_perm:[1,0,3,2] row_mask:0xf bank_mask:0xf
	v_perm_b32 v16, v17, v16, v84
	v_perm_b32 v64, v65, v64, v84
	v_perm_b32 v48, v49, v48, v84
	v_perm_b32 v32, v33, v32, v84
	global_store_dword v82, v16, s[6:7]
	global_store_dword v82, v64, s[6:7] offset:64
	global_store_dword v82, v48, s[6:7] offset:128
	global_store_dword v82, v32, s[6:7] offset:192
	s_branch .LBB0_1292
